# v52 + final rmsnorm phase hand-rewritten: 8 rows (32 KB) per wave in flight with counted vmcnt instead of 1-row lookahead
# baseline (speedup 1.0000x reference)
.LBB0_2457:
	s_cmp_lt_i32 s86, 14
	s_cselect_b64 s[0:1], -1, 0
	s_and_b64 s[0:1], s[0:1], s[2:3]
	s_andn2_b64 vcc, exec, s[0:1]
	s_cbranch_vccnz .LBB0_2461
	s_mov_b32 s6, 0x8000
	v_cmp_gt_i32_e32 vcc, s6, v176
	s_and_saveexec_b64 s[0:1], vcc
	s_cbranch_execz .LBB0_2461
	v_and_b32_e32 v0, 63, v222
	v_lshlrev_b32_e32 v34, 4, v0
	v_readfirstlane_b32 s10, v176
	s_waitcnt lgkmcnt(0)
	global_load_dwordx4 v[0:3], v34, s[80:81]
	global_load_dwordx4 v[4:7], v34, s[80:81] offset:1024
	global_load_dwordx4 v[8:11], v34, s[80:81] offset:2048
	global_load_dwordx4 v[12:15], v34, s[80:81] offset:3072
	v_mbcnt_lo_u32_b32 v35, -1, 0
	v_mbcnt_hi_u32_b32 v35, -1, v35
	v_xor_b32_e32 v38, 1, v35
	v_xor_b32_e32 v39, 2, v35
	v_xor_b32_e32 v40, 4, v35
	v_xor_b32_e32 v41, 8, v35
	v_xor_b32_e32 v42, 16, v35
	v_xor_b32_e32 v43, 32, v35
	v_lshlrev_b32_e32 v38, 2, v38
	v_lshlrev_b32_e32 v39, 2, v39
	v_lshlrev_b32_e32 v40, 2, v40
	v_lshlrev_b32_e32 v41, 2, v41
	v_lshlrev_b32_e32 v42, 2, v42
	v_lshlrev_b32_e32 v43, 2, v43
	v_mov_b32_e32 v36, 0x358637bd
	v_mov_b32_e32 v37, 0x260
	s_mov_b32 s8, 0xf800000
	s_lshl_b32 s11, s56, 12
.Lfn_group:
	s_mov_b32 s40, s10
	s_add_u32 s41, s40, s56
	s_add_u32 s42, s41, s56
	s_add_u32 s43, s42, s56
	s_add_u32 s44, s43, s56
	s_add_u32 s45, s44, s56
	s_add_u32 s46, s45, s56
	s_add_u32 s47, s46, s56
	s_cmp_lt_u32 s40, s6
	s_cselect_b32 s12, s40, s10
	s_lshl_b32 s12, s12, 12
	s_add_u32 s16, s82, s12
	s_addc_u32 s17, s83, 0
	s_cmp_lt_u32 s41, s6
	s_cselect_b32 s12, s41, s10
	s_lshl_b32 s12, s12, 12
	s_add_u32 s18, s82, s12
	s_addc_u32 s19, s83, 0
	s_cmp_lt_u32 s42, s6
	s_cselect_b32 s12, s42, s10
	s_lshl_b32 s12, s12, 12
	s_add_u32 s20, s82, s12
	s_addc_u32 s21, s83, 0
	s_cmp_lt_u32 s43, s6
	s_cselect_b32 s12, s43, s10
	s_lshl_b32 s12, s12, 12
	s_add_u32 s22, s82, s12
	s_addc_u32 s23, s83, 0
	s_cmp_lt_u32 s44, s6
	s_cselect_b32 s12, s44, s10
	s_lshl_b32 s12, s12, 12
	s_add_u32 s24, s82, s12
	s_addc_u32 s25, s83, 0
	s_cmp_lt_u32 s45, s6
	s_cselect_b32 s12, s45, s10
	s_lshl_b32 s12, s12, 12
	s_add_u32 s26, s82, s12
	s_addc_u32 s27, s83, 0
	s_cmp_lt_u32 s46, s6
	s_cselect_b32 s12, s46, s10
	s_lshl_b32 s12, s12, 12
	s_add_u32 s28, s82, s12
	s_addc_u32 s29, s83, 0
	s_cmp_lt_u32 s47, s6
	s_cselect_b32 s12, s47, s10
	s_lshl_b32 s12, s12, 12
	s_add_u32 s30, s82, s12
	s_addc_u32 s31, s83, 0
	global_load_dwordx4 v[64:67], v34, s[16:17]
	global_load_dwordx4 v[68:71], v34, s[16:17] offset:1024
	global_load_dwordx4 v[72:75], v34, s[16:17] offset:2048
	global_load_dwordx4 v[76:79], v34, s[16:17] offset:3072
	global_load_dwordx4 v[80:83], v34, s[18:19]
	global_load_dwordx4 v[84:87], v34, s[18:19] offset:1024
	global_load_dwordx4 v[88:91], v34, s[18:19] offset:2048
	global_load_dwordx4 v[92:95], v34, s[18:19] offset:3072
	global_load_dwordx4 v[96:99], v34, s[20:21]
	global_load_dwordx4 v[100:103], v34, s[20:21] offset:1024
	global_load_dwordx4 v[104:107], v34, s[20:21] offset:2048
	global_load_dwordx4 v[108:111], v34, s[20:21] offset:3072
	global_load_dwordx4 v[112:115], v34, s[22:23]
	global_load_dwordx4 v[116:119], v34, s[22:23] offset:1024
	global_load_dwordx4 v[120:123], v34, s[22:23] offset:2048
	global_load_dwordx4 v[124:127], v34, s[22:23] offset:3072
	global_load_dwordx4 v[128:131], v34, s[24:25]
	global_load_dwordx4 v[132:135], v34, s[24:25] offset:1024
	global_load_dwordx4 v[136:139], v34, s[24:25] offset:2048
	global_load_dwordx4 v[140:143], v34, s[24:25] offset:3072
	global_load_dwordx4 v[144:147], v34, s[26:27]
	global_load_dwordx4 v[148:151], v34, s[26:27] offset:1024
	global_load_dwordx4 v[152:155], v34, s[26:27] offset:2048
	global_load_dwordx4 v[156:159], v34, s[26:27] offset:3072
	global_load_dwordx4 v[160:163], v34, s[28:29]
	global_load_dwordx4 v[164:167], v34, s[28:29] offset:1024
	global_load_dwordx4 v[168:171], v34, s[28:29] offset:2048
	global_load_dwordx4 v[172:175], v34, s[28:29] offset:3072
	global_load_dwordx4 v[176:179], v34, s[30:31]
	global_load_dwordx4 v[180:183], v34, s[30:31] offset:1024
	global_load_dwordx4 v[184:187], v34, s[30:31] offset:2048
	global_load_dwordx4 v[188:191], v34, s[30:31] offset:3072
	s_waitcnt vmcnt(28)
	v_mul_f32_e32 v16, v64, v64
	v_mul_f32_e32 v17, v66, v66
	v_fmac_f32_e32 v16, v65, v65
	v_fmac_f32_e32 v17, v67, v67
	v_mul_f32_e32 v18, v68, v68
	v_mul_f32_e32 v19, v70, v70
	v_fmac_f32_e32 v18, v69, v69
	v_fmac_f32_e32 v19, v71, v71
	v_mul_f32_e32 v20, v72, v72
	v_mul_f32_e32 v21, v74, v74
	v_fmac_f32_e32 v20, v73, v73
	v_fmac_f32_e32 v21, v75, v75
	v_mul_f32_e32 v22, v76, v76
	v_mul_f32_e32 v23, v78, v78
	v_fmac_f32_e32 v22, v77, v77
	v_fmac_f32_e32 v23, v79, v79
	v_add_f32_e32 v16, v16, v17
	v_add_f32_e32 v18, v18, v19
	v_add_f32_e32 v20, v20, v21
	v_add_f32_e32 v22, v22, v23
	v_add_f32_e32 v16, v16, v18
	v_add_f32_e32 v16, v16, v20
	v_add_f32_e32 v16, v16, v22
	ds_bpermute_b32 v17, v38, v16
	s_waitcnt lgkmcnt(0)
	v_add_f32_e32 v16, v16, v17
	ds_bpermute_b32 v17, v39, v16
	s_waitcnt lgkmcnt(0)
	v_add_f32_e32 v16, v16, v17
	ds_bpermute_b32 v17, v40, v16
	s_waitcnt lgkmcnt(0)
	v_add_f32_e32 v16, v16, v17
	ds_bpermute_b32 v17, v41, v16
	s_waitcnt lgkmcnt(0)
	v_add_f32_e32 v16, v16, v17
	ds_bpermute_b32 v17, v42, v16
	s_waitcnt lgkmcnt(0)
	v_add_f32_e32 v16, v16, v17
	ds_bpermute_b32 v17, v43, v16
	s_waitcnt lgkmcnt(0)
	v_add_f32_e32 v16, v16, v17
	v_fmamk_f32 v16, v16, 0x3a800000, v36
	v_mul_f32_e32 v17, 0x4f800000, v16
	v_cmp_gt_f32_e32 vcc, s8, v16
	s_nop 1
	v_cndmask_b32_e32 v16, v16, v17, vcc
	v_sqrt_f32_e32 v17, v16
	s_nop 0
	v_add_u32_e32 v18, -1, v17
	v_add_u32_e32 v19, 1, v17
	v_fma_f32 v20, -v18, v17, v16
	v_fma_f32 v21, -v19, v17, v16
	v_cmp_ge_f32_e64 s[0:1], 0, v20
	s_nop 1
	v_cndmask_b32_e64 v17, v17, v18, s[0:1]
	v_cmp_lt_f32_e64 s[0:1], 0, v21
	s_nop 1
	v_cndmask_b32_e64 v17, v17, v19, s[0:1]
	v_mul_f32_e32 v18, 0x37800000, v17
	v_cndmask_b32_e32 v17, v17, v18, vcc
	v_cmp_class_f32_e32 vcc, v16, v37
	s_nop 1
	v_cndmask_b32_e32 v16, v17, v16, vcc
	v_div_scale_f32 v17, s[0:1], v16, v16, 1.0
	v_rcp_f32_e32 v19, v17
	v_div_scale_f32 v18, vcc, 1.0, v16, 1.0
	v_fma_f32 v20, -v17, v19, 1.0
	v_fmac_f32_e32 v19, v20, v19
	v_mul_f32_e32 v20, v18, v19
	v_fma_f32 v21, -v17, v20, v18
	v_fmac_f32_e32 v20, v21, v19
	v_fma_f32 v17, -v17, v20, v18
	v_div_fmas_f32 v17, v17, v19, v20
	v_div_fixup_f32 v16, v17, v16, 1.0
	v_pk_mul_f32 v[64:65], v[64:65], v[16:17] op_sel_hi:[1,0]
	v_pk_mul_f32 v[66:67], v[66:67], v[16:17] op_sel_hi:[1,0]
	v_pk_mul_f32 v[68:69], v[68:69], v[16:17] op_sel_hi:[1,0]
	v_pk_mul_f32 v[70:71], v[70:71], v[16:17] op_sel_hi:[1,0]
	v_pk_mul_f32 v[72:73], v[72:73], v[16:17] op_sel_hi:[1,0]
	v_pk_mul_f32 v[74:75], v[74:75], v[16:17] op_sel_hi:[1,0]
	v_pk_mul_f32 v[76:77], v[76:77], v[16:17] op_sel_hi:[1,0]
	v_pk_mul_f32 v[78:79], v[78:79], v[16:17] op_sel_hi:[1,0]
	v_pk_mul_f32 v[64:65], v[0:1], v[64:65]
	v_pk_mul_f32 v[66:67], v[2:3], v[66:67]
	v_pk_mul_f32 v[68:69], v[4:5], v[68:69]
	v_pk_mul_f32 v[70:71], v[6:7], v[70:71]
	v_pk_mul_f32 v[72:73], v[8:9], v[72:73]
	v_pk_mul_f32 v[74:75], v[10:11], v[74:75]
	v_pk_mul_f32 v[76:77], v[12:13], v[76:77]
	v_pk_mul_f32 v[78:79], v[14:15], v[78:79]
	global_store_dwordx4 v34, v[64:67], s[16:17]
	global_store_dwordx4 v34, v[68:71], s[16:17] offset:1024
	global_store_dwordx4 v34, v[72:75], s[16:17] offset:2048
	global_store_dwordx4 v34, v[76:79], s[16:17] offset:3072
	s_cmp_lt_u32 s41, s6
	s_cbranch_scc0 .Lfn_exit
	s_waitcnt vmcnt(28)
	v_mul_f32_e32 v16, v80, v80
	v_mul_f32_e32 v17, v82, v82
	v_fmac_f32_e32 v16, v81, v81
	v_fmac_f32_e32 v17, v83, v83
	v_mul_f32_e32 v18, v84, v84
	v_mul_f32_e32 v19, v86, v86
	v_fmac_f32_e32 v18, v85, v85
	v_fmac_f32_e32 v19, v87, v87
	v_mul_f32_e32 v20, v88, v88
	v_mul_f32_e32 v21, v90, v90
	v_fmac_f32_e32 v20, v89, v89
	v_fmac_f32_e32 v21, v91, v91
	v_mul_f32_e32 v22, v92, v92
	v_mul_f32_e32 v23, v94, v94
	v_fmac_f32_e32 v22, v93, v93
	v_fmac_f32_e32 v23, v95, v95
	v_add_f32_e32 v16, v16, v17
	v_add_f32_e32 v18, v18, v19
	v_add_f32_e32 v20, v20, v21
	v_add_f32_e32 v22, v22, v23
	v_add_f32_e32 v16, v16, v18
	v_add_f32_e32 v16, v16, v20
	v_add_f32_e32 v16, v16, v22
	ds_bpermute_b32 v17, v38, v16
	s_waitcnt lgkmcnt(0)
	v_add_f32_e32 v16, v16, v17
	ds_bpermute_b32 v17, v39, v16
	s_waitcnt lgkmcnt(0)
	v_add_f32_e32 v16, v16, v17
	ds_bpermute_b32 v17, v40, v16
	s_waitcnt lgkmcnt(0)
	v_add_f32_e32 v16, v16, v17
	ds_bpermute_b32 v17, v41, v16
	s_waitcnt lgkmcnt(0)
	v_add_f32_e32 v16, v16, v17
	ds_bpermute_b32 v17, v42, v16
	s_waitcnt lgkmcnt(0)
	v_add_f32_e32 v16, v16, v17
	ds_bpermute_b32 v17, v43, v16
	s_waitcnt lgkmcnt(0)
	v_add_f32_e32 v16, v16, v17
	v_fmamk_f32 v16, v16, 0x3a800000, v36
	v_mul_f32_e32 v17, 0x4f800000, v16
	v_cmp_gt_f32_e32 vcc, s8, v16
	s_nop 1
	v_cndmask_b32_e32 v16, v16, v17, vcc
	v_sqrt_f32_e32 v17, v16
	s_nop 0
	v_add_u32_e32 v18, -1, v17
	v_add_u32_e32 v19, 1, v17
	v_fma_f32 v20, -v18, v17, v16
	v_fma_f32 v21, -v19, v17, v16
	v_cmp_ge_f32_e64 s[0:1], 0, v20
	s_nop 1
	v_cndmask_b32_e64 v17, v17, v18, s[0:1]
	v_cmp_lt_f32_e64 s[0:1], 0, v21
	s_nop 1
	v_cndmask_b32_e64 v17, v17, v19, s[0:1]
	v_mul_f32_e32 v18, 0x37800000, v17
	v_cndmask_b32_e32 v17, v17, v18, vcc
	v_cmp_class_f32_e32 vcc, v16, v37
	s_nop 1
	v_cndmask_b32_e32 v16, v17, v16, vcc
	v_div_scale_f32 v17, s[0:1], v16, v16, 1.0
	v_rcp_f32_e32 v19, v17
	v_div_scale_f32 v18, vcc, 1.0, v16, 1.0
	v_fma_f32 v20, -v17, v19, 1.0
	v_fmac_f32_e32 v19, v20, v19
	v_mul_f32_e32 v20, v18, v19
	v_fma_f32 v21, -v17, v20, v18
	v_fmac_f32_e32 v20, v21, v19
	v_fma_f32 v17, -v17, v20, v18
	v_div_fmas_f32 v17, v17, v19, v20
	v_div_fixup_f32 v16, v17, v16, 1.0
	v_pk_mul_f32 v[80:81], v[80:81], v[16:17] op_sel_hi:[1,0]
	v_pk_mul_f32 v[82:83], v[82:83], v[16:17] op_sel_hi:[1,0]
	v_pk_mul_f32 v[84:85], v[84:85], v[16:17] op_sel_hi:[1,0]
	v_pk_mul_f32 v[86:87], v[86:87], v[16:17] op_sel_hi:[1,0]
	v_pk_mul_f32 v[88:89], v[88:89], v[16:17] op_sel_hi:[1,0]
	v_pk_mul_f32 v[90:91], v[90:91], v[16:17] op_sel_hi:[1,0]
	v_pk_mul_f32 v[92:93], v[92:93], v[16:17] op_sel_hi:[1,0]
	v_pk_mul_f32 v[94:95], v[94:95], v[16:17] op_sel_hi:[1,0]
	v_pk_mul_f32 v[80:81], v[0:1], v[80:81]
	v_pk_mul_f32 v[82:83], v[2:3], v[82:83]
	v_pk_mul_f32 v[84:85], v[4:5], v[84:85]
	v_pk_mul_f32 v[86:87], v[6:7], v[86:87]
	v_pk_mul_f32 v[88:89], v[8:9], v[88:89]
	v_pk_mul_f32 v[90:91], v[10:11], v[90:91]
	v_pk_mul_f32 v[92:93], v[12:13], v[92:93]
	v_pk_mul_f32 v[94:95], v[14:15], v[94:95]
	global_store_dwordx4 v34, v[80:83], s[18:19]
	global_store_dwordx4 v34, v[84:87], s[18:19] offset:1024
	global_store_dwordx4 v34, v[88:91], s[18:19] offset:2048
	global_store_dwordx4 v34, v[92:95], s[18:19] offset:3072
	s_cmp_lt_u32 s42, s6
	s_cbranch_scc0 .Lfn_exit
	s_waitcnt vmcnt(28)
	v_mul_f32_e32 v16, v96, v96
	v_mul_f32_e32 v17, v98, v98
	v_fmac_f32_e32 v16, v97, v97
	v_fmac_f32_e32 v17, v99, v99
	v_mul_f32_e32 v18, v100, v100
	v_mul_f32_e32 v19, v102, v102
	v_fmac_f32_e32 v18, v101, v101
	v_fmac_f32_e32 v19, v103, v103
	v_mul_f32_e32 v20, v104, v104
	v_mul_f32_e32 v21, v106, v106
	v_fmac_f32_e32 v20, v105, v105
	v_fmac_f32_e32 v21, v107, v107
	v_mul_f32_e32 v22, v108, v108
	v_mul_f32_e32 v23, v110, v110
	v_fmac_f32_e32 v22, v109, v109
	v_fmac_f32_e32 v23, v111, v111
	v_add_f32_e32 v16, v16, v17
	v_add_f32_e32 v18, v18, v19
	v_add_f32_e32 v20, v20, v21
	v_add_f32_e32 v22, v22, v23
	v_add_f32_e32 v16, v16, v18
	v_add_f32_e32 v16, v16, v20
	v_add_f32_e32 v16, v16, v22
	ds_bpermute_b32 v17, v38, v16
	s_waitcnt lgkmcnt(0)
	v_add_f32_e32 v16, v16, v17
	ds_bpermute_b32 v17, v39, v16
	s_waitcnt lgkmcnt(0)
	v_add_f32_e32 v16, v16, v17
	ds_bpermute_b32 v17, v40, v16
	s_waitcnt lgkmcnt(0)
	v_add_f32_e32 v16, v16, v17
	ds_bpermute_b32 v17, v41, v16
	s_waitcnt lgkmcnt(0)
	v_add_f32_e32 v16, v16, v17
	ds_bpermute_b32 v17, v42, v16
	s_waitcnt lgkmcnt(0)
	v_add_f32_e32 v16, v16, v17
	ds_bpermute_b32 v17, v43, v16
	s_waitcnt lgkmcnt(0)
	v_add_f32_e32 v16, v16, v17
	v_fmamk_f32 v16, v16, 0x3a800000, v36
	v_mul_f32_e32 v17, 0x4f800000, v16
	v_cmp_gt_f32_e32 vcc, s8, v16
	s_nop 1
	v_cndmask_b32_e32 v16, v16, v17, vcc
	v_sqrt_f32_e32 v17, v16
	s_nop 0
	v_add_u32_e32 v18, -1, v17
	v_add_u32_e32 v19, 1, v17
	v_fma_f32 v20, -v18, v17, v16
	v_fma_f32 v21, -v19, v17, v16
	v_cmp_ge_f32_e64 s[0:1], 0, v20
	s_nop 1
	v_cndmask_b32_e64 v17, v17, v18, s[0:1]
	v_cmp_lt_f32_e64 s[0:1], 0, v21
	s_nop 1
	v_cndmask_b32_e64 v17, v17, v19, s[0:1]
	v_mul_f32_e32 v18, 0x37800000, v17
	v_cndmask_b32_e32 v17, v17, v18, vcc
	v_cmp_class_f32_e32 vcc, v16, v37
	s_nop 1
	v_cndmask_b32_e32 v16, v17, v16, vcc
	v_div_scale_f32 v17, s[0:1], v16, v16, 1.0
	v_rcp_f32_e32 v19, v17
	v_div_scale_f32 v18, vcc, 1.0, v16, 1.0
	v_fma_f32 v20, -v17, v19, 1.0
	v_fmac_f32_e32 v19, v20, v19
	v_mul_f32_e32 v20, v18, v19
	v_fma_f32 v21, -v17, v20, v18
	v_fmac_f32_e32 v20, v21, v19
	v_fma_f32 v17, -v17, v20, v18
	v_div_fmas_f32 v17, v17, v19, v20
	v_div_fixup_f32 v16, v17, v16, 1.0
	v_pk_mul_f32 v[96:97], v[96:97], v[16:17] op_sel_hi:[1,0]
	v_pk_mul_f32 v[98:99], v[98:99], v[16:17] op_sel_hi:[1,0]
	v_pk_mul_f32 v[100:101], v[100:101], v[16:17] op_sel_hi:[1,0]
	v_pk_mul_f32 v[102:103], v[102:103], v[16:17] op_sel_hi:[1,0]
	v_pk_mul_f32 v[104:105], v[104:105], v[16:17] op_sel_hi:[1,0]
	v_pk_mul_f32 v[106:107], v[106:107], v[16:17] op_sel_hi:[1,0]
	v_pk_mul_f32 v[108:109], v[108:109], v[16:17] op_sel_hi:[1,0]
	v_pk_mul_f32 v[110:111], v[110:111], v[16:17] op_sel_hi:[1,0]
	v_pk_mul_f32 v[96:97], v[0:1], v[96:97]
	v_pk_mul_f32 v[98:99], v[2:3], v[98:99]
	v_pk_mul_f32 v[100:101], v[4:5], v[100:101]
	v_pk_mul_f32 v[102:103], v[6:7], v[102:103]
	v_pk_mul_f32 v[104:105], v[8:9], v[104:105]
	v_pk_mul_f32 v[106:107], v[10:11], v[106:107]
	v_pk_mul_f32 v[108:109], v[12:13], v[108:109]
	v_pk_mul_f32 v[110:111], v[14:15], v[110:111]
	global_store_dwordx4 v34, v[96:99], s[20:21]
	global_store_dwordx4 v34, v[100:103], s[20:21] offset:1024
	global_store_dwordx4 v34, v[104:107], s[20:21] offset:2048
	global_store_dwordx4 v34, v[108:111], s[20:21] offset:3072
	s_cmp_lt_u32 s43, s6
	s_cbranch_scc0 .Lfn_exit
	s_waitcnt vmcnt(28)
	v_mul_f32_e32 v16, v112, v112
	v_mul_f32_e32 v17, v114, v114
	v_fmac_f32_e32 v16, v113, v113
	v_fmac_f32_e32 v17, v115, v115
	v_mul_f32_e32 v18, v116, v116
	v_mul_f32_e32 v19, v118, v118
	v_fmac_f32_e32 v18, v117, v117
	v_fmac_f32_e32 v19, v119, v119
	v_mul_f32_e32 v20, v120, v120
	v_mul_f32_e32 v21, v122, v122
	v_fmac_f32_e32 v20, v121, v121
	v_fmac_f32_e32 v21, v123, v123
	v_mul_f32_e32 v22, v124, v124
	v_mul_f32_e32 v23, v126, v126
	v_fmac_f32_e32 v22, v125, v125
	v_fmac_f32_e32 v23, v127, v127
	v_add_f32_e32 v16, v16, v17
	v_add_f32_e32 v18, v18, v19
	v_add_f32_e32 v20, v20, v21
	v_add_f32_e32 v22, v22, v23
	v_add_f32_e32 v16, v16, v18
	v_add_f32_e32 v16, v16, v20
	v_add_f32_e32 v16, v16, v22
	ds_bpermute_b32 v17, v38, v16
	s_waitcnt lgkmcnt(0)
	v_add_f32_e32 v16, v16, v17
	ds_bpermute_b32 v17, v39, v16
	s_waitcnt lgkmcnt(0)
	v_add_f32_e32 v16, v16, v17
	ds_bpermute_b32 v17, v40, v16
	s_waitcnt lgkmcnt(0)
	v_add_f32_e32 v16, v16, v17
	ds_bpermute_b32 v17, v41, v16
	s_waitcnt lgkmcnt(0)
	v_add_f32_e32 v16, v16, v17
	ds_bpermute_b32 v17, v42, v16
	s_waitcnt lgkmcnt(0)
	v_add_f32_e32 v16, v16, v17
	ds_bpermute_b32 v17, v43, v16
	s_waitcnt lgkmcnt(0)
	v_add_f32_e32 v16, v16, v17
	v_fmamk_f32 v16, v16, 0x3a800000, v36
	v_mul_f32_e32 v17, 0x4f800000, v16
	v_cmp_gt_f32_e32 vcc, s8, v16
	s_nop 1
	v_cndmask_b32_e32 v16, v16, v17, vcc
	v_sqrt_f32_e32 v17, v16
	s_nop 0
	v_add_u32_e32 v18, -1, v17
	v_add_u32_e32 v19, 1, v17
	v_fma_f32 v20, -v18, v17, v16
	v_fma_f32 v21, -v19, v17, v16
	v_cmp_ge_f32_e64 s[0:1], 0, v20
	s_nop 1
	v_cndmask_b32_e64 v17, v17, v18, s[0:1]
	v_cmp_lt_f32_e64 s[0:1], 0, v21
	s_nop 1
	v_cndmask_b32_e64 v17, v17, v19, s[0:1]
	v_mul_f32_e32 v18, 0x37800000, v17
	v_cndmask_b32_e32 v17, v17, v18, vcc
	v_cmp_class_f32_e32 vcc, v16, v37
	s_nop 1
	v_cndmask_b32_e32 v16, v17, v16, vcc
	v_div_scale_f32 v17, s[0:1], v16, v16, 1.0
	v_rcp_f32_e32 v19, v17
	v_div_scale_f32 v18, vcc, 1.0, v16, 1.0
	v_fma_f32 v20, -v17, v19, 1.0
	v_fmac_f32_e32 v19, v20, v19
	v_mul_f32_e32 v20, v18, v19
	v_fma_f32 v21, -v17, v20, v18
	v_fmac_f32_e32 v20, v21, v19
	v_fma_f32 v17, -v17, v20, v18
	v_div_fmas_f32 v17, v17, v19, v20
	v_div_fixup_f32 v16, v17, v16, 1.0
	v_pk_mul_f32 v[112:113], v[112:113], v[16:17] op_sel_hi:[1,0]
	v_pk_mul_f32 v[114:115], v[114:115], v[16:17] op_sel_hi:[1,0]
	v_pk_mul_f32 v[116:117], v[116:117], v[16:17] op_sel_hi:[1,0]
	v_pk_mul_f32 v[118:119], v[118:119], v[16:17] op_sel_hi:[1,0]
	v_pk_mul_f32 v[120:121], v[120:121], v[16:17] op_sel_hi:[1,0]
	v_pk_mul_f32 v[122:123], v[122:123], v[16:17] op_sel_hi:[1,0]
	v_pk_mul_f32 v[124:125], v[124:125], v[16:17] op_sel_hi:[1,0]
	v_pk_mul_f32 v[126:127], v[126:127], v[16:17] op_sel_hi:[1,0]
	v_pk_mul_f32 v[112:113], v[0:1], v[112:113]
	v_pk_mul_f32 v[114:115], v[2:3], v[114:115]
	v_pk_mul_f32 v[116:117], v[4:5], v[116:117]
	v_pk_mul_f32 v[118:119], v[6:7], v[118:119]
	v_pk_mul_f32 v[120:121], v[8:9], v[120:121]
	v_pk_mul_f32 v[122:123], v[10:11], v[122:123]
	v_pk_mul_f32 v[124:125], v[12:13], v[124:125]
	v_pk_mul_f32 v[126:127], v[14:15], v[126:127]
	global_store_dwordx4 v34, v[112:115], s[22:23]
	global_store_dwordx4 v34, v[116:119], s[22:23] offset:1024
	global_store_dwordx4 v34, v[120:123], s[22:23] offset:2048
	global_store_dwordx4 v34, v[124:127], s[22:23] offset:3072
	s_cmp_lt_u32 s44, s6
	s_cbranch_scc0 .Lfn_exit
	s_waitcnt vmcnt(28)
	v_mul_f32_e32 v16, v128, v128
	v_mul_f32_e32 v17, v130, v130
	v_fmac_f32_e32 v16, v129, v129
	v_fmac_f32_e32 v17, v131, v131
	v_mul_f32_e32 v18, v132, v132
	v_mul_f32_e32 v19, v134, v134
	v_fmac_f32_e32 v18, v133, v133
	v_fmac_f32_e32 v19, v135, v135
	v_mul_f32_e32 v20, v136, v136
	v_mul_f32_e32 v21, v138, v138
	v_fmac_f32_e32 v20, v137, v137
	v_fmac_f32_e32 v21, v139, v139
	v_mul_f32_e32 v22, v140, v140
	v_mul_f32_e32 v23, v142, v142
	v_fmac_f32_e32 v22, v141, v141
	v_fmac_f32_e32 v23, v143, v143
	v_add_f32_e32 v16, v16, v17
	v_add_f32_e32 v18, v18, v19
	v_add_f32_e32 v20, v20, v21
	v_add_f32_e32 v22, v22, v23
	v_add_f32_e32 v16, v16, v18
	v_add_f32_e32 v16, v16, v20
	v_add_f32_e32 v16, v16, v22
	ds_bpermute_b32 v17, v38, v16
	s_waitcnt lgkmcnt(0)
	v_add_f32_e32 v16, v16, v17
	ds_bpermute_b32 v17, v39, v16
	s_waitcnt lgkmcnt(0)
	v_add_f32_e32 v16, v16, v17
	ds_bpermute_b32 v17, v40, v16
	s_waitcnt lgkmcnt(0)
	v_add_f32_e32 v16, v16, v17
	ds_bpermute_b32 v17, v41, v16
	s_waitcnt lgkmcnt(0)
	v_add_f32_e32 v16, v16, v17
	ds_bpermute_b32 v17, v42, v16
	s_waitcnt lgkmcnt(0)
	v_add_f32_e32 v16, v16, v17
	ds_bpermute_b32 v17, v43, v16
	s_waitcnt lgkmcnt(0)
	v_add_f32_e32 v16, v16, v17
	v_fmamk_f32 v16, v16, 0x3a800000, v36
	v_mul_f32_e32 v17, 0x4f800000, v16
	v_cmp_gt_f32_e32 vcc, s8, v16
	s_nop 1
	v_cndmask_b32_e32 v16, v16, v17, vcc
	v_sqrt_f32_e32 v17, v16
	s_nop 0
	v_add_u32_e32 v18, -1, v17
	v_add_u32_e32 v19, 1, v17
	v_fma_f32 v20, -v18, v17, v16
	v_fma_f32 v21, -v19, v17, v16
	v_cmp_ge_f32_e64 s[0:1], 0, v20
	s_nop 1
	v_cndmask_b32_e64 v17, v17, v18, s[0:1]
	v_cmp_lt_f32_e64 s[0:1], 0, v21
	s_nop 1
	v_cndmask_b32_e64 v17, v17, v19, s[0:1]
	v_mul_f32_e32 v18, 0x37800000, v17
	v_cndmask_b32_e32 v17, v17, v18, vcc
	v_cmp_class_f32_e32 vcc, v16, v37
	s_nop 1
	v_cndmask_b32_e32 v16, v17, v16, vcc
	v_div_scale_f32 v17, s[0:1], v16, v16, 1.0
	v_rcp_f32_e32 v19, v17
	v_div_scale_f32 v18, vcc, 1.0, v16, 1.0
	v_fma_f32 v20, -v17, v19, 1.0
	v_fmac_f32_e32 v19, v20, v19
	v_mul_f32_e32 v20, v18, v19
	v_fma_f32 v21, -v17, v20, v18
	v_fmac_f32_e32 v20, v21, v19
	v_fma_f32 v17, -v17, v20, v18
	v_div_fmas_f32 v17, v17, v19, v20
	v_div_fixup_f32 v16, v17, v16, 1.0
	v_pk_mul_f32 v[128:129], v[128:129], v[16:17] op_sel_hi:[1,0]
	v_pk_mul_f32 v[130:131], v[130:131], v[16:17] op_sel_hi:[1,0]
	v_pk_mul_f32 v[132:133], v[132:133], v[16:17] op_sel_hi:[1,0]
	v_pk_mul_f32 v[134:135], v[134:135], v[16:17] op_sel_hi:[1,0]
	v_pk_mul_f32 v[136:137], v[136:137], v[16:17] op_sel_hi:[1,0]
	v_pk_mul_f32 v[138:139], v[138:139], v[16:17] op_sel_hi:[1,0]
	v_pk_mul_f32 v[140:141], v[140:141], v[16:17] op_sel_hi:[1,0]
	v_pk_mul_f32 v[142:143], v[142:143], v[16:17] op_sel_hi:[1,0]
	v_pk_mul_f32 v[128:129], v[0:1], v[128:129]
	v_pk_mul_f32 v[130:131], v[2:3], v[130:131]
	v_pk_mul_f32 v[132:133], v[4:5], v[132:133]
	v_pk_mul_f32 v[134:135], v[6:7], v[134:135]
	v_pk_mul_f32 v[136:137], v[8:9], v[136:137]
	v_pk_mul_f32 v[138:139], v[10:11], v[138:139]
	v_pk_mul_f32 v[140:141], v[12:13], v[140:141]
	v_pk_mul_f32 v[142:143], v[14:15], v[142:143]
	global_store_dwordx4 v34, v[128:131], s[24:25]
	global_store_dwordx4 v34, v[132:135], s[24:25] offset:1024
	global_store_dwordx4 v34, v[136:139], s[24:25] offset:2048
	global_store_dwordx4 v34, v[140:143], s[24:25] offset:3072
	s_cmp_lt_u32 s45, s6
	s_cbranch_scc0 .Lfn_exit
	s_waitcnt vmcnt(28)
	v_mul_f32_e32 v16, v144, v144
	v_mul_f32_e32 v17, v146, v146
	v_fmac_f32_e32 v16, v145, v145
	v_fmac_f32_e32 v17, v147, v147
	v_mul_f32_e32 v18, v148, v148
	v_mul_f32_e32 v19, v150, v150
	v_fmac_f32_e32 v18, v149, v149
	v_fmac_f32_e32 v19, v151, v151
	v_mul_f32_e32 v20, v152, v152
	v_mul_f32_e32 v21, v154, v154
	v_fmac_f32_e32 v20, v153, v153
	v_fmac_f32_e32 v21, v155, v155
	v_mul_f32_e32 v22, v156, v156
	v_mul_f32_e32 v23, v158, v158
	v_fmac_f32_e32 v22, v157, v157
	v_fmac_f32_e32 v23, v159, v159
	v_add_f32_e32 v16, v16, v17
	v_add_f32_e32 v18, v18, v19
	v_add_f32_e32 v20, v20, v21
	v_add_f32_e32 v22, v22, v23
	v_add_f32_e32 v16, v16, v18
	v_add_f32_e32 v16, v16, v20
	v_add_f32_e32 v16, v16, v22
	ds_bpermute_b32 v17, v38, v16
	s_waitcnt lgkmcnt(0)
	v_add_f32_e32 v16, v16, v17
	ds_bpermute_b32 v17, v39, v16
	s_waitcnt lgkmcnt(0)
	v_add_f32_e32 v16, v16, v17
	ds_bpermute_b32 v17, v40, v16
	s_waitcnt lgkmcnt(0)
	v_add_f32_e32 v16, v16, v17
	ds_bpermute_b32 v17, v41, v16
	s_waitcnt lgkmcnt(0)
	v_add_f32_e32 v16, v16, v17
	ds_bpermute_b32 v17, v42, v16
	s_waitcnt lgkmcnt(0)
	v_add_f32_e32 v16, v16, v17
	ds_bpermute_b32 v17, v43, v16
	s_waitcnt lgkmcnt(0)
	v_add_f32_e32 v16, v16, v17
	v_fmamk_f32 v16, v16, 0x3a800000, v36
	v_mul_f32_e32 v17, 0x4f800000, v16
	v_cmp_gt_f32_e32 vcc, s8, v16
	s_nop 1
	v_cndmask_b32_e32 v16, v16, v17, vcc
	v_sqrt_f32_e32 v17, v16
	s_nop 0
	v_add_u32_e32 v18, -1, v17
	v_add_u32_e32 v19, 1, v17
	v_fma_f32 v20, -v18, v17, v16
	v_fma_f32 v21, -v19, v17, v16
	v_cmp_ge_f32_e64 s[0:1], 0, v20
	s_nop 1
	v_cndmask_b32_e64 v17, v17, v18, s[0:1]
	v_cmp_lt_f32_e64 s[0:1], 0, v21
	s_nop 1
	v_cndmask_b32_e64 v17, v17, v19, s[0:1]
	v_mul_f32_e32 v18, 0x37800000, v17
	v_cndmask_b32_e32 v17, v17, v18, vcc
	v_cmp_class_f32_e32 vcc, v16, v37
	s_nop 1
	v_cndmask_b32_e32 v16, v17, v16, vcc
	v_div_scale_f32 v17, s[0:1], v16, v16, 1.0
	v_rcp_f32_e32 v19, v17
	v_div_scale_f32 v18, vcc, 1.0, v16, 1.0
	v_fma_f32 v20, -v17, v19, 1.0
	v_fmac_f32_e32 v19, v20, v19
	v_mul_f32_e32 v20, v18, v19
	v_fma_f32 v21, -v17, v20, v18
	v_fmac_f32_e32 v20, v21, v19
	v_fma_f32 v17, -v17, v20, v18
	v_div_fmas_f32 v17, v17, v19, v20
	v_div_fixup_f32 v16, v17, v16, 1.0
	v_pk_mul_f32 v[144:145], v[144:145], v[16:17] op_sel_hi:[1,0]
	v_pk_mul_f32 v[146:147], v[146:147], v[16:17] op_sel_hi:[1,0]
	v_pk_mul_f32 v[148:149], v[148:149], v[16:17] op_sel_hi:[1,0]
	v_pk_mul_f32 v[150:151], v[150:151], v[16:17] op_sel_hi:[1,0]
	v_pk_mul_f32 v[152:153], v[152:153], v[16:17] op_sel_hi:[1,0]
	v_pk_mul_f32 v[154:155], v[154:155], v[16:17] op_sel_hi:[1,0]
	v_pk_mul_f32 v[156:157], v[156:157], v[16:17] op_sel_hi:[1,0]
	v_pk_mul_f32 v[158:159], v[158:159], v[16:17] op_sel_hi:[1,0]
	v_pk_mul_f32 v[144:145], v[0:1], v[144:145]
	v_pk_mul_f32 v[146:147], v[2:3], v[146:147]
	v_pk_mul_f32 v[148:149], v[4:5], v[148:149]
	v_pk_mul_f32 v[150:151], v[6:7], v[150:151]
	v_pk_mul_f32 v[152:153], v[8:9], v[152:153]
	v_pk_mul_f32 v[154:155], v[10:11], v[154:155]
	v_pk_mul_f32 v[156:157], v[12:13], v[156:157]
	v_pk_mul_f32 v[158:159], v[14:15], v[158:159]
	global_store_dwordx4 v34, v[144:147], s[26:27]
	global_store_dwordx4 v34, v[148:151], s[26:27] offset:1024
	global_store_dwordx4 v34, v[152:155], s[26:27] offset:2048
	global_store_dwordx4 v34, v[156:159], s[26:27] offset:3072
	s_cmp_lt_u32 s46, s6
	s_cbranch_scc0 .Lfn_exit
	s_waitcnt vmcnt(28)
	v_mul_f32_e32 v16, v160, v160
	v_mul_f32_e32 v17, v162, v162
	v_fmac_f32_e32 v16, v161, v161
	v_fmac_f32_e32 v17, v163, v163
	v_mul_f32_e32 v18, v164, v164
	v_mul_f32_e32 v19, v166, v166
	v_fmac_f32_e32 v18, v165, v165
	v_fmac_f32_e32 v19, v167, v167
	v_mul_f32_e32 v20, v168, v168
	v_mul_f32_e32 v21, v170, v170
	v_fmac_f32_e32 v20, v169, v169
	v_fmac_f32_e32 v21, v171, v171
	v_mul_f32_e32 v22, v172, v172
	v_mul_f32_e32 v23, v174, v174
	v_fmac_f32_e32 v22, v173, v173
	v_fmac_f32_e32 v23, v175, v175
	v_add_f32_e32 v16, v16, v17
	v_add_f32_e32 v18, v18, v19
	v_add_f32_e32 v20, v20, v21
	v_add_f32_e32 v22, v22, v23
	v_add_f32_e32 v16, v16, v18
	v_add_f32_e32 v16, v16, v20
	v_add_f32_e32 v16, v16, v22
	ds_bpermute_b32 v17, v38, v16
	s_waitcnt lgkmcnt(0)
	v_add_f32_e32 v16, v16, v17
	ds_bpermute_b32 v17, v39, v16
	s_waitcnt lgkmcnt(0)
	v_add_f32_e32 v16, v16, v17
	ds_bpermute_b32 v17, v40, v16
	s_waitcnt lgkmcnt(0)
	v_add_f32_e32 v16, v16, v17
	ds_bpermute_b32 v17, v41, v16
	s_waitcnt lgkmcnt(0)
	v_add_f32_e32 v16, v16, v17
	ds_bpermute_b32 v17, v42, v16
	s_waitcnt lgkmcnt(0)
	v_add_f32_e32 v16, v16, v17
	ds_bpermute_b32 v17, v43, v16
	s_waitcnt lgkmcnt(0)
	v_add_f32_e32 v16, v16, v17
	v_fmamk_f32 v16, v16, 0x3a800000, v36
	v_mul_f32_e32 v17, 0x4f800000, v16
	v_cmp_gt_f32_e32 vcc, s8, v16
	s_nop 1
	v_cndmask_b32_e32 v16, v16, v17, vcc
	v_sqrt_f32_e32 v17, v16
	s_nop 0
	v_add_u32_e32 v18, -1, v17
	v_add_u32_e32 v19, 1, v17
	v_fma_f32 v20, -v18, v17, v16
	v_fma_f32 v21, -v19, v17, v16
	v_cmp_ge_f32_e64 s[0:1], 0, v20
	s_nop 1
	v_cndmask_b32_e64 v17, v17, v18, s[0:1]
	v_cmp_lt_f32_e64 s[0:1], 0, v21
	s_nop 1
	v_cndmask_b32_e64 v17, v17, v19, s[0:1]
	v_mul_f32_e32 v18, 0x37800000, v17
	v_cndmask_b32_e32 v17, v17, v18, vcc
	v_cmp_class_f32_e32 vcc, v16, v37
	s_nop 1
	v_cndmask_b32_e32 v16, v17, v16, vcc
	v_div_scale_f32 v17, s[0:1], v16, v16, 1.0
	v_rcp_f32_e32 v19, v17
	v_div_scale_f32 v18, vcc, 1.0, v16, 1.0
	v_fma_f32 v20, -v17, v19, 1.0
	v_fmac_f32_e32 v19, v20, v19
	v_mul_f32_e32 v20, v18, v19
	v_fma_f32 v21, -v17, v20, v18
	v_fmac_f32_e32 v20, v21, v19
	v_fma_f32 v17, -v17, v20, v18
	v_div_fmas_f32 v17, v17, v19, v20
	v_div_fixup_f32 v16, v17, v16, 1.0
	v_pk_mul_f32 v[160:161], v[160:161], v[16:17] op_sel_hi:[1,0]
	v_pk_mul_f32 v[162:163], v[162:163], v[16:17] op_sel_hi:[1,0]
	v_pk_mul_f32 v[164:165], v[164:165], v[16:17] op_sel_hi:[1,0]
	v_pk_mul_f32 v[166:167], v[166:167], v[16:17] op_sel_hi:[1,0]
	v_pk_mul_f32 v[168:169], v[168:169], v[16:17] op_sel_hi:[1,0]
	v_pk_mul_f32 v[170:171], v[170:171], v[16:17] op_sel_hi:[1,0]
	v_pk_mul_f32 v[172:173], v[172:173], v[16:17] op_sel_hi:[1,0]
	v_pk_mul_f32 v[174:175], v[174:175], v[16:17] op_sel_hi:[1,0]
	v_pk_mul_f32 v[160:161], v[0:1], v[160:161]
	v_pk_mul_f32 v[162:163], v[2:3], v[162:163]
	v_pk_mul_f32 v[164:165], v[4:5], v[164:165]
	v_pk_mul_f32 v[166:167], v[6:7], v[166:167]
	v_pk_mul_f32 v[168:169], v[8:9], v[168:169]
	v_pk_mul_f32 v[170:171], v[10:11], v[170:171]
	v_pk_mul_f32 v[172:173], v[12:13], v[172:173]
	v_pk_mul_f32 v[174:175], v[14:15], v[174:175]
	global_store_dwordx4 v34, v[160:163], s[28:29]
	global_store_dwordx4 v34, v[164:167], s[28:29] offset:1024
	global_store_dwordx4 v34, v[168:171], s[28:29] offset:2048
	global_store_dwordx4 v34, v[172:175], s[28:29] offset:3072
	s_cmp_lt_u32 s47, s6
	s_cbranch_scc0 .Lfn_exit
	s_waitcnt vmcnt(28)
	v_mul_f32_e32 v16, v176, v176
	v_mul_f32_e32 v17, v178, v178
	v_fmac_f32_e32 v16, v177, v177
	v_fmac_f32_e32 v17, v179, v179
	v_mul_f32_e32 v18, v180, v180
	v_mul_f32_e32 v19, v182, v182
	v_fmac_f32_e32 v18, v181, v181
	v_fmac_f32_e32 v19, v183, v183
	v_mul_f32_e32 v20, v184, v184
	v_mul_f32_e32 v21, v186, v186
	v_fmac_f32_e32 v20, v185, v185
	v_fmac_f32_e32 v21, v187, v187
	v_mul_f32_e32 v22, v188, v188
	v_mul_f32_e32 v23, v190, v190
	v_fmac_f32_e32 v22, v189, v189
	v_fmac_f32_e32 v23, v191, v191
	v_add_f32_e32 v16, v16, v17
	v_add_f32_e32 v18, v18, v19
	v_add_f32_e32 v20, v20, v21
	v_add_f32_e32 v22, v22, v23
	v_add_f32_e32 v16, v16, v18
	v_add_f32_e32 v16, v16, v20
	v_add_f32_e32 v16, v16, v22
	ds_bpermute_b32 v17, v38, v16
	s_waitcnt lgkmcnt(0)
	v_add_f32_e32 v16, v16, v17
	ds_bpermute_b32 v17, v39, v16
	s_waitcnt lgkmcnt(0)
	v_add_f32_e32 v16, v16, v17
	ds_bpermute_b32 v17, v40, v16
	s_waitcnt lgkmcnt(0)
	v_add_f32_e32 v16, v16, v17
	ds_bpermute_b32 v17, v41, v16
	s_waitcnt lgkmcnt(0)
	v_add_f32_e32 v16, v16, v17
	ds_bpermute_b32 v17, v42, v16
	s_waitcnt lgkmcnt(0)
	v_add_f32_e32 v16, v16, v17
	ds_bpermute_b32 v17, v43, v16
	s_waitcnt lgkmcnt(0)
	v_add_f32_e32 v16, v16, v17
	v_fmamk_f32 v16, v16, 0x3a800000, v36
	v_mul_f32_e32 v17, 0x4f800000, v16
	v_cmp_gt_f32_e32 vcc, s8, v16
	s_nop 1
	v_cndmask_b32_e32 v16, v16, v17, vcc
	v_sqrt_f32_e32 v17, v16
	s_nop 0
	v_add_u32_e32 v18, -1, v17
	v_add_u32_e32 v19, 1, v17
	v_fma_f32 v20, -v18, v17, v16
	v_fma_f32 v21, -v19, v17, v16
	v_cmp_ge_f32_e64 s[0:1], 0, v20
	s_nop 1
	v_cndmask_b32_e64 v17, v17, v18, s[0:1]
	v_cmp_lt_f32_e64 s[0:1], 0, v21
	s_nop 1
	v_cndmask_b32_e64 v17, v17, v19, s[0:1]
	v_mul_f32_e32 v18, 0x37800000, v17
	v_cndmask_b32_e32 v17, v17, v18, vcc
	v_cmp_class_f32_e32 vcc, v16, v37
	s_nop 1
	v_cndmask_b32_e32 v16, v17, v16, vcc
	v_div_scale_f32 v17, s[0:1], v16, v16, 1.0
	v_rcp_f32_e32 v19, v17
	v_div_scale_f32 v18, vcc, 1.0, v16, 1.0
	v_fma_f32 v20, -v17, v19, 1.0
	v_fmac_f32_e32 v19, v20, v19
	v_mul_f32_e32 v20, v18, v19
	v_fma_f32 v21, -v17, v20, v18
	v_fmac_f32_e32 v20, v21, v19
	v_fma_f32 v17, -v17, v20, v18
	v_div_fmas_f32 v17, v17, v19, v20
	v_div_fixup_f32 v16, v17, v16, 1.0
	v_pk_mul_f32 v[176:177], v[176:177], v[16:17] op_sel_hi:[1,0]
	v_pk_mul_f32 v[178:179], v[178:179], v[16:17] op_sel_hi:[1,0]
	v_pk_mul_f32 v[180:181], v[180:181], v[16:17] op_sel_hi:[1,0]
	v_pk_mul_f32 v[182:183], v[182:183], v[16:17] op_sel_hi:[1,0]
	v_pk_mul_f32 v[184:185], v[184:185], v[16:17] op_sel_hi:[1,0]
	v_pk_mul_f32 v[186:187], v[186:187], v[16:17] op_sel_hi:[1,0]
	v_pk_mul_f32 v[188:189], v[188:189], v[16:17] op_sel_hi:[1,0]
	v_pk_mul_f32 v[190:191], v[190:191], v[16:17] op_sel_hi:[1,0]
	v_pk_mul_f32 v[176:177], v[0:1], v[176:177]
	v_pk_mul_f32 v[178:179], v[2:3], v[178:179]
	v_pk_mul_f32 v[180:181], v[4:5], v[180:181]
	v_pk_mul_f32 v[182:183], v[6:7], v[182:183]
	v_pk_mul_f32 v[184:185], v[8:9], v[184:185]
	v_pk_mul_f32 v[186:187], v[10:11], v[186:187]
	v_pk_mul_f32 v[188:189], v[12:13], v[188:189]
	v_pk_mul_f32 v[190:191], v[14:15], v[190:191]
	global_store_dwordx4 v34, v[176:179], s[30:31]
	global_store_dwordx4 v34, v[180:183], s[30:31] offset:1024
	global_store_dwordx4 v34, v[184:187], s[30:31] offset:2048
	global_store_dwordx4 v34, v[188:191], s[30:31] offset:3072
	s_add_u32 s10, s47, s56
	s_cmp_lt_u32 s10, s6
	s_cbranch_scc1 .Lfn_group
.Lfn_exit:
.LBB0_2461:
	s_endpgm
